# P1: compress GEMM via LDS-DMA B image + 2 A slices in flight + early compress on half the workgroups; P3 selected stream: list/mask reads hoisted to once per stage, stage priority by active-tile count
# speedup vs baseline: 1.0040x; 1.0040x over previous
; #define LAS __attribute__((address_space(3)))
; #define SS_ISSUE(t, slot) do { LAS unsigned char* d_ = lbase + (slot) * 2 * TILEB; const size_t gb_ = (size_t)rowfn(t) * 256 + goff; \
;         __builtin_amdgcn_global_load_lds((const unsigned*)((const char*)Kg + gb_), (LAS unsigned*)d_, 16, 0, 0); \
;         __builtin_amdgcn_global_load_lds((const unsigned*)((const char*)Vg + gb_), (LAS unsigned*)(d_ + TILEB), 16, 0, 0); } while (0)
; template <int NB, class RowFn, class Compute>
; DEV void stream_stages_dma(Frame& F, int n, const bf16* Kg, const bf16* Vg, RowFn rowfn, Compute compute) {
;     ...
;     for (int i0 = 0, st = 0; i0 < n; i0 += NB, st ^= 1) {
;         asm volatile("s_waitcnt vmcnt(0)" ::: "memory");
;         __builtin_amdgcn_s_barrier(); asm volatile("" ::: "memory");
; #pragma unroll
;         for (int b = 0; b < NB; ++b) if (i0 + NB + b < n) SS_ISSUE(i0 + NB + b, (st ^ 1) * NB + b);
;         const LAS unsigned char* cur = F.lds + st * NB * 2 * TILEB;
; #pragma unroll
;         for (int b = 0; b < NB; ++b) if (i0 + b < n) compute(i0 + b, cur + b * 2 * TILEB, cur + b * 2 * TILEB + TILEB);
; DEV void attn_unit_mfma(Frame& F, int qg, int kv) {
;     ...
;         const int j = lst[1 + i]; const unsigned byte = (msk[2 * j + (w >> 2)] >> (8 * (w & 3))) & 0xffu;
;         const bool a0 = (byte & 0xfu) != 0u, a1 = (byte & 0xf0u) != 0u;
.LBB0_1171:
	s_waitcnt lgkmcnt(0)
	v_mov_b32_e32 v66, s24
	ds_read_b32 v67, v66
	ds_read_b32 v68, v66 offset:4
	ds_read_b32 v69, v66 offset:8
	s_waitcnt lgkmcnt(0)
	v_lshl_add_u32 v70, v67, 3, s2
	v_lshl_add_u32 v71, v68, 3, s2
	v_lshl_add_u32 v72, v69, 3, s2
	ds_read_b32 v70, v70
	ds_read_b32 v71, v71
	ds_read_b32 v72, v72
	v_readfirstlane_b32 s98, v67
	v_readfirstlane_b32 s99, v68
	v_readfirstlane_b32 s100, v69
	s_waitcnt lgkmcnt(0)
	v_readfirstlane_b32 s9, v70
	v_readfirstlane_b32 s10, v71
	v_readfirstlane_b32 s11, v72
	s_and_b32 s98, s98, 0xffff
	s_and_b32 s99, s99, 0xffff
	s_and_b32 s100, s100, 0xffff
	s_lshr_b32 s9, s9, s33
	s_and_b32 s9, s9, 0xff
	s_lshl_b32 s9, s9, 16
	s_or_b32 s98, s98, s9
	s_lshr_b32 s10, s10, s33
	s_and_b32 s10, s10, 0xff
	s_lshl_b32 s10, s10, 16
	s_or_b32 s99, s99, s10
	s_lshr_b32 s11, s11, s33
	s_and_b32 s11, s11, 0xff
	s_lshl_b32 s11, s11, 16
	s_or_b32 s100, s100, s11
	s_lshr_b32 s9, s98, 16
	s_cmp_lg_u32 s9, 0
	s_cselect_b32 s9, 1, 0
	s_lshr_b32 s10, s99, 16
	s_cmp_lg_u32 s10, 0
	s_cselect_b32 s10, 1, 0
	s_lshr_b32 s11, s100, 16
	s_cmp_lg_u32 s11, 0
	s_cselect_b32 s11, 1, 0
	s_add_i32 s12, s28, -1
	s_cmp_lt_i32 s12, s23
	s_cselect_b32 s10, s10, 0
	s_cmp_lt_i32 s28, s23
	s_cselect_b32 s11, s11, 0
	s_add_i32 s9, s9, s10
	s_add_i32 s9, s9, s11
	s_cmp_ge_u32 s9, 3
	s_cbranch_scc0 .Lmy_sel_p2
	s_setprio 2
	s_branch .Lmy_sel_pd
.Lmy_sel_p2:
	s_cmp_eq_u32 s9, 2
	s_cbranch_scc0 .Lmy_sel_p1
	s_setprio 1
	s_branch .Lmy_sel_pd
.Lmy_sel_p1:
	s_setprio 0
; #define LAS __attribute__((address_space(3)))
; #define NEG_INF (-__builtin_inff())
; DEV void qk64(const LAS unsigned char* Kb, const AttnCtx& C, const ab8 (&qf)[2][2], f32x4 (&s)[2][4], float init0, float init1, bool a0, bool a1) {
;     ab8 k0[4], k1[4];
; #pragma unroll
;     for (int kt = 0; kt < 4; ++kt) { k0[kt] = *(const LAS ab8*)(Kb + swz(16 * kt + C.n, C.q4)); k1[kt] = *(const LAS ab8*)(Kb + swz(16 * kt + C.n, 4 + C.q4)); }
;     __builtin_amdgcn_sched_barrier(0);
; #pragma unroll
;     for (int kt = 0; kt < 4; ++kt) {
;         if (a0) { f32x4 c = {init0, init0, init0, init0}; c = __builtin_amdgcn_mfma_f32_16x16x32_bf16(k0[kt], qf[0][0], c, 0, 0, 0); s[0][kt] = __builtin_amdgcn_mfma_f32_16x16x32_bf16(k1[kt], qf[0][1], c, 0, 0, 0); }
;         if (a1) { f32x4 c = {init1, init1, init1, init1}; c = __builtin_amdgcn_mfma_f32_16x16x32_bf16(k0[kt], qf[1][0], c, 0, 0, 0); s[1][kt] = __builtin_amdgcn_mfma_f32_16x16x32_bf16(k1[kt], qf[1][1], c, 0, 0, 0); }
;     }
; }
; template <bool LUTB, bool WINLO>
; DEV void mask_bias(f32x4 (&s)[4], const AttnCtx& C, int t, int p0, int pstep, bool colok) {
; #pragma unroll
;     for (int kt = 0; kt < 4; ++kt)
; #pragma unroll
;         for (int i = 0; i < 4; ++i) { const int rel = t - (p0 + pstep * (16 * kt + 4 * C.q4 + i));
;             bool ok = colok && rel >= 0; if (WINLO) ok = ok && rel < 512;
;             float v = s[kt][i]; if (LUTB) v += C.lut[C.h * 129 + (rel < 0 ? 0 : (rel < 128 ? rel : 128))];
;             s[kt][i] = ok ? v : NEG_INF; }
; }
; DEV void attn_unit_mfma(Frame& F, int qg, int kv) {
;     ...
;         const int j = lst[1 + i]; const unsigned byte = (msk[2 * j + (w >> 2)] >> (8 * (w & 3))) & 0xffu;
;         const bool a0 = (byte & 0xfu) != 0u, a1 = (byte & 0xf0u) != 0u;
;         if (a0 || a1) {
;             const bool near = j >= cur - 2; const float bi = near ? 0.f : C.b31;
;             const bool c0 = ((byte >> (C.n >> 2)) & 1u) != 0u, c1 = ((byte >> (4 + (C.n >> 2))) & 1u) != 0u;
;     ...
;             if (a0 && a1) SEL_BODY(true, true); else if (a0) SEL_BODY(true, false); else SEL_BODY(false, true);
.Lmy_sel_pd:
	s_mul_i32 s8, s8, 0xc000
	s_add_i32 s9, s28, -2
	s_add_i32 s27, s8, 0
	s_cmp_ge_i32 s9, s23
	s_cbranch_scc1 .LBB0_1196
	s_waitcnt lgkmcnt(0)
	s_and_b32 s29, s98, 0xffff
	s_lshr_b32 s8, s98, 16
	s_and_b32 s9, s8, 0xff
	s_cmp_eq_u32 s9, 0
	s_cbranch_scc1 .LBB0_1196
	s_and_b32 s9, s8, 15
	s_cmp_eq_u32 s9, 0
	s_cselect_b64 s[14:15], -1, 0
	s_and_b32 s9, s8, 0xf0
	s_cmp_eq_u32 s9, 0
	s_cselect_b64 s[12:13], -1, 0
	s_cmp_ge_i32 s29, s22
	s_cselect_b64 s[18:19], -1, 0
	s_cmp_lt_i32 s29, s22
	v_and_b32_e32 v66, s8, v206
	s_cselect_b64 vcc, -1, 0
	v_cmp_ne_u32_e64 s[10:11], 0, v66
	v_and_b32_e32 v66, s8, v207
	s_or_b64 s[16:17], s[14:15], s[12:13]
	v_cndmask_b32_e32 v214, 0, v175, vcc
	v_cmp_ne_u32_e64 s[8:9], 0, v66
	s_mov_b64 s[12:13], -1
	s_and_b64 vcc, exec, s[16:17]
	s_cbranch_vccz .LBB0_1186
	v_add3_u32 v66, s27, v199, v198
	v_add3_u32 v67, s27, v197, v198
	ds_read_b128 v[70:73], v66
	ds_read_b128 v[74:77], v66 offset:2048
	ds_read_b128 v[90:93], v67
	ds_read_b128 v[78:81], v67 offset:2048
	ds_read_b128 v[82:85], v66 offset:4096
	ds_read_b128 v[86:89], v66 offset:6144
	ds_read_b128 v[94:97], v67 offset:4096
	ds_read_b128 v[66:69], v67 offset:6144
	s_and_b64 vcc, exec, s[14:15]
	s_cbranch_vccz .LBB0_1180
	v_cmp_eq_f32_e64 s[12:13], s3, v212
	s_nop 1
	v_cndmask_b32_e64 v98, v212, 0, s[12:13]
	v_sub_f32_e32 v98, v214, v98
	v_cndmask_b32_e64 v102, v173, v98, s[8:9]
	v_mov_b32_e32 v103, v102
	v_mov_b32_e32 v104, v102
	v_mov_b32_e32 v105, v102
	s_andn2_b64 vcc, exec, s[18:19]
	s_waitcnt lgkmcnt(0)
	v_mfma_f32_16x16x32_bf16 v[98:101], v[70:73], v[10:13], v[102:105]
	v_mfma_f32_16x16x32_bf16 v[110:113], v[90:93], v[14:17], v[98:101]
	v_mfma_f32_16x16x32_bf16 v[98:101], v[74:77], v[10:13], v[102:105]
	v_mfma_f32_16x16x32_bf16 v[106:109], v[78:81], v[14:17], v[98:101]
	v_mfma_f32_16x16x32_bf16 v[98:101], v[82:85], v[10:13], v[102:105]
	v_mfma_f32_16x16x32_bf16 v[102:105], v[86:89], v[10:13], v[102:105]
	v_mfma_f32_16x16x32_bf16 v[98:101], v[94:97], v[14:17], v[98:101]
	v_mfma_f32_16x16x32_bf16 v[102:105], v[66:69], v[14:17], v[102:105]
	s_cbranch_vccnz .LBB0_1177
	s_lshl_b32 s14, s29, 6
	v_subrev_u32_e32 v122, s14, v144
	v_sub_u32_e32 v123, v122, v20
	v_add_u32_e32 v124, v122, v208
	v_add_u32_e32 v125, -3, v123
	v_add_u32_e32 v126, -2, v123
	v_subrev_u32_e32 v127, 17, v123
	v_add_u32_e32 v128, -16, v123
	v_subrev_u32_e32 v129, 33, v123
	v_subrev_u32_e32 v130, 32, v123
	v_med3_i32 v114, v123, 0, v172
	v_med3_i32 v115, v124, 0, v172
	v_med3_i32 v116, v126, 0, v172
	v_med3_i32 v117, v125, 0, v172
	v_med3_i32 v118, v128, 0, v172
	v_med3_i32 v119, v127, 0, v172
	v_med3_i32 v120, v130, 0, v172
	v_med3_i32 v121, v129, 0, v172
	v_lshl_add_u32 v114, v114, 2, v174
	v_lshl_add_u32 v115, v115, 2, v174
	v_lshl_add_u32 v116, v116, 2, v174
	v_lshl_add_u32 v117, v117, 2, v174
	v_lshl_add_u32 v118, v118, 2, v174
	v_lshl_add_u32 v119, v119, 2, v174
	v_lshl_add_u32 v120, v120, 2, v174
	v_lshl_add_u32 v121, v121, 2, v174
	ds_read_b32 v114, v114
	ds_read_b32 v115, v115
	ds_read_b32 v116, v116
	ds_read_b32 v117, v117
	ds_read_b32 v118, v118
	ds_read_b32 v119, v119
	ds_read_b32 v120, v120
	ds_read_b32 v121, v121
	s_waitcnt lgkmcnt(0)
	v_pk_add_f32 v[110:111], v[110:111], v[114:115]
	v_cmp_lt_i32_e32 vcc, -1, v124
	v_pk_add_f32 v[112:113], v[112:113], v[116:117]
	v_sub_u32_e32 v116, v122, v158
	v_cndmask_b32_e32 v111, v173, v111, vcc
	v_cmp_lt_i32_e32 vcc, -1, v123
	v_sub_u32_e32 v117, v122, v1
	v_subrev_u32_e32 v124, 49, v123
	v_cndmask_b32_e32 v110, v173, v110, vcc
	v_cmp_lt_i32_e32 vcc, -1, v125
	v_subrev_u32_e32 v125, 48, v123
	v_add_u32_e32 v131, -16, v116
	v_cndmask_b32_e32 v113, v173, v113, vcc
	v_cmp_lt_i32_e32 vcc, -1, v126
	v_add_u32_e32 v126, -16, v117
	v_subrev_u32_e32 v132, 32, v117
	v_subrev_u32_e32 v133, 32, v116
	v_subrev_u32_e32 v135, 48, v116
	v_med3_i32 v114, v125, 0, v172
	v_med3_i32 v115, v124, 0, v172
	v_med3_i32 v122, v131, 0, v172
	v_med3_i32 v123, v126, 0, v172
	v_pk_add_f32 v[106:107], v[106:107], v[118:119]
	v_med3_i32 v118, v133, 0, v172
	v_med3_i32 v119, v132, 0, v172
	v_subrev_u32_e32 v134, 48, v117
	v_med3_i32 v116, v135, 0, v172
	v_lshl_add_u32 v114, v114, 2, v174
	v_lshl_add_u32 v115, v115, 2, v174
	v_lshl_add_u32 v122, v122, 2, v174
	v_lshl_add_u32 v123, v123, 2, v174
	v_lshl_add_u32 v118, v118, 2, v174
	v_lshl_add_u32 v119, v119, 2, v174
	v_lshl_add_u32 v136, v116, 2, v174
	v_med3_i32 v116, v134, 0, v172
	v_lshl_add_u32 v137, v116, 2, v174
	ds_read_b32 v114, v114
	ds_read_b32 v115, v115
	ds_read_b32 v116, v122
	ds_read_b32 v117, v123
	ds_read_b32 v118, v118
	ds_read_b32 v119, v119
	ds_read_b32 v122, v136
	ds_read_b32 v123, v137
	v_cndmask_b32_e32 v112, v173, v112, vcc
	s_waitcnt lgkmcnt(0)
	v_pk_add_f32 v[108:109], v[108:109], v[116:117]
	v_cmp_lt_i32_e32 vcc, -1, v126
	v_pk_add_f32 v[100:101], v[100:101], v[118:119]
	v_pk_add_f32 v[98:99], v[98:99], v[120:121]
	v_cndmask_b32_e32 v109, v173, v109, vcc
	v_cmp_lt_i32_e32 vcc, -1, v131
	v_pk_add_f32 v[104:105], v[104:105], v[122:123]
	v_pk_add_f32 v[102:103], v[102:103], v[114:115]
	v_cndmask_b32_e32 v108, v173, v108, vcc
	v_cmp_lt_i32_e32 vcc, -1, v127
	s_nop 1
	v_cndmask_b32_e32 v107, v173, v107, vcc
	v_cmp_lt_i32_e32 vcc, -1, v128
	s_nop 1
	v_cndmask_b32_e32 v106, v173, v106, vcc
	v_cmp_lt_i32_e32 vcc, -1, v132
	s_nop 1
	v_cndmask_b32_e32 v101, v173, v101, vcc
	v_cmp_lt_i32_e32 vcc, -1, v133
	s_nop 1
	v_cndmask_b32_e32 v100, v173, v100, vcc
	v_cmp_lt_i32_e32 vcc, -1, v129
	s_nop 1
	v_cndmask_b32_e32 v99, v173, v99, vcc
	v_cmp_lt_i32_e32 vcc, -1, v130
	s_nop 1
	v_cndmask_b32_e32 v98, v173, v98, vcc
	v_cmp_lt_i32_e32 vcc, -1, v134
	s_nop 1
	v_cndmask_b32_e32 v105, v173, v105, vcc
	v_cmp_lt_i32_e32 vcc, -1, v135
	s_nop 1
	v_cndmask_b32_e32 v104, v173, v104, vcc
	v_cmp_lt_i32_e32 vcc, -1, v124
	s_nop 1
	v_cndmask_b32_e32 v103, v173, v103, vcc
	v_cmp_lt_i32_e32 vcc, -1, v125
	s_nop 1
	v_cndmask_b32_e32 v102, v173, v102, vcc

; #define LAS __attribute__((address_space(3)))
; #define NEG_INF (-__builtin_inff())
; DEV void qk64(const LAS unsigned char* Kb, const AttnCtx& C, const ab8 (&qf)[2][2], f32x4 (&s)[2][4], float init0, float init1, bool a0, bool a1) {
;     ab8 k0[4], k1[4];
; #pragma unroll
;     for (int kt = 0; kt < 4; ++kt) { k0[kt] = *(const LAS ab8*)(Kb + swz(16 * kt + C.n, C.q4)); k1[kt] = *(const LAS ab8*)(Kb + swz(16 * kt + C.n, 4 + C.q4)); }
;     __builtin_amdgcn_sched_barrier(0);
; #pragma unroll
;     for (int kt = 0; kt < 4; ++kt) {
;         if (a0) { f32x4 c = {init0, init0, init0, init0}; c = __builtin_amdgcn_mfma_f32_16x16x32_bf16(k0[kt], qf[0][0], c, 0, 0, 0); s[0][kt] = __builtin_amdgcn_mfma_f32_16x16x32_bf16(k1[kt], qf[0][1], c, 0, 0, 0); }
;         if (a1) { f32x4 c = {init1, init1, init1, init1}; c = __builtin_amdgcn_mfma_f32_16x16x32_bf16(k0[kt], qf[1][0], c, 0, 0, 0); s[1][kt] = __builtin_amdgcn_mfma_f32_16x16x32_bf16(k1[kt], qf[1][1], c, 0, 0, 0); }
;     }
; }
; template <bool LUTB, bool WINLO>
; DEV void mask_bias(f32x4 (&s)[4], const AttnCtx& C, int t, int p0, int pstep, bool colok) {
; #pragma unroll
;     for (int kt = 0; kt < 4; ++kt)
; #pragma unroll
;         for (int i = 0; i < 4; ++i) { const int rel = t - (p0 + pstep * (16 * kt + 4 * C.q4 + i));
;             bool ok = colok && rel >= 0; if (WINLO) ok = ok && rel < 512;
;             float v = s[kt][i]; if (LUTB) v += C.lut[C.h * 129 + (rel < 0 ? 0 : (rel < 128 ? rel : 128))];
;             s[kt][i] = ok ? v : NEG_INF; }
; }
; DEV void attn_unit_mfma(Frame& F, int qg, int kv) {
;     ...
;         const int j = lst[1 + i]; const unsigned byte = (msk[2 * j + (w >> 2)] >> (8 * (w & 3))) & 0xffu;
;         const bool a0 = (byte & 0xfu) != 0u, a1 = (byte & 0xf0u) != 0u;
;         if (a0 || a1) {
;             const bool near = j >= cur - 2; const float bi = near ? 0.f : C.b31;
;             const bool c0 = ((byte >> (C.n >> 2)) & 1u) != 0u, c1 = ((byte >> (4 + (C.n >> 2))) & 1u) != 0u;
;     ...
;             if (a0 && a1) SEL_BODY(true, true); else if (a0) SEL_BODY(true, false); else SEL_BODY(false, true);
.LBB0_1196:
	s_add_i32 s8, s28, -1
	s_cmp_ge_i32 s8, s23
	s_cbranch_scc1 .LBB0_1222
	s_waitcnt lgkmcnt(0)
	s_and_b32 s29, s99, 0xffff
	s_lshr_b32 s8, s99, 16
	s_and_b32 s9, s8, 0xff
	s_cmp_eq_u32 s9, 0
	s_cbranch_scc1 .LBB0_1222
	s_and_b32 s9, s8, 15
	s_cmp_eq_u32 s9, 0
	s_cselect_b64 s[12:13], -1, 0
	s_cmp_lg_u32 s9, 0
	s_cselect_b64 s[14:15], -1, 0
	s_and_b32 s9, s8, 0xf0
	s_cmp_lg_u32 s9, 0
	s_cselect_b64 s[16:17], -1, 0
	s_cmp_ge_i32 s29, s22
	s_cselect_b64 s[18:19], -1, 0
	s_cmp_lt_i32 s29, s22
	v_and_b32_e32 v66, s8, v206
	s_cselect_b64 vcc, -1, 0
	v_cmp_ne_u32_e64 s[10:11], 0, v66
	v_and_b32_e32 v66, s8, v207
	s_and_b64 s[16:17], s[14:15], s[16:17]
	v_cndmask_b32_e32 v214, 0, v175, vcc
	v_cmp_ne_u32_e64 s[8:9], 0, v66
	s_mov_b64 s[14:15], -1
	s_and_b64 vcc, exec, s[16:17]
	s_cbranch_vccnz .LBB0_1212
	v_add3_u32 v66, s27, v199, v198
	v_add3_u32 v67, s27, v197, v198
	ds_read_b128 v[70:73], v66 offset:16384
	ds_read_b128 v[74:77], v66 offset:18432
	ds_read_b128 v[90:93], v67 offset:16384
	ds_read_b128 v[78:81], v67 offset:18432
	ds_read_b128 v[82:85], v66 offset:20480
	ds_read_b128 v[86:89], v66 offset:22528
	ds_read_b128 v[94:97], v67 offset:20480
	ds_read_b128 v[66:69], v67 offset:22528
	s_andn2_b64 vcc, exec, s[12:13]
	s_mov_b64 s[12:13], -1
	s_cbranch_vccnz .LBB0_1205
	v_cmp_eq_f32_e64 s[12:13], s3, v212
	s_nop 1
	v_cndmask_b32_e64 v98, v212, 0, s[12:13]
	v_sub_f32_e32 v98, v214, v98
	v_cndmask_b32_e64 v102, v173, v98, s[8:9]
	v_mov_b32_e32 v103, v102
	v_mov_b32_e32 v104, v102
	v_mov_b32_e32 v105, v102
	s_andn2_b64 vcc, exec, s[18:19]
	s_waitcnt lgkmcnt(0)
	v_mfma_f32_16x16x32_bf16 v[98:101], v[70:73], v[10:13], v[102:105]
	v_mfma_f32_16x16x32_bf16 v[110:113], v[90:93], v[14:17], v[98:101]
	v_mfma_f32_16x16x32_bf16 v[98:101], v[74:77], v[10:13], v[102:105]
	v_mfma_f32_16x16x32_bf16 v[106:109], v[78:81], v[14:17], v[98:101]
	v_mfma_f32_16x16x32_bf16 v[98:101], v[82:85], v[10:13], v[102:105]
	v_mfma_f32_16x16x32_bf16 v[102:105], v[86:89], v[10:13], v[102:105]
	v_mfma_f32_16x16x32_bf16 v[98:101], v[94:97], v[14:17], v[98:101]
	v_mfma_f32_16x16x32_bf16 v[102:105], v[66:69], v[14:17], v[102:105]
	s_cbranch_vccnz .LBB0_1202
	s_lshl_b32 s14, s29, 6
	v_subrev_u32_e32 v122, s14, v144
	v_sub_u32_e32 v123, v122, v20
	v_add_u32_e32 v124, v122, v208
	v_add_u32_e32 v125, -3, v123
	v_add_u32_e32 v126, -2, v123
	v_subrev_u32_e32 v127, 17, v123
	v_add_u32_e32 v128, -16, v123
	v_subrev_u32_e32 v129, 33, v123
	v_subrev_u32_e32 v130, 32, v123
	v_med3_i32 v114, v123, 0, v172
	v_med3_i32 v115, v124, 0, v172
	v_med3_i32 v116, v126, 0, v172
	v_med3_i32 v117, v125, 0, v172
	v_med3_i32 v118, v128, 0, v172
	v_med3_i32 v119, v127, 0, v172
	v_med3_i32 v120, v130, 0, v172
	v_med3_i32 v121, v129, 0, v172
	v_lshl_add_u32 v114, v114, 2, v174
	v_lshl_add_u32 v115, v115, 2, v174
	v_lshl_add_u32 v116, v116, 2, v174
	v_lshl_add_u32 v117, v117, 2, v174
	v_lshl_add_u32 v118, v118, 2, v174
	v_lshl_add_u32 v119, v119, 2, v174
	v_lshl_add_u32 v120, v120, 2, v174
	v_lshl_add_u32 v121, v121, 2, v174
	ds_read_b32 v114, v114
	ds_read_b32 v115, v115
	ds_read_b32 v116, v116
	ds_read_b32 v117, v117
	ds_read_b32 v118, v118
	ds_read_b32 v119, v119
	ds_read_b32 v120, v120
	ds_read_b32 v121, v121
	s_waitcnt lgkmcnt(0)
	v_pk_add_f32 v[110:111], v[110:111], v[114:115]
	v_cmp_lt_i32_e32 vcc, -1, v124
	v_pk_add_f32 v[112:113], v[112:113], v[116:117]
	v_sub_u32_e32 v116, v122, v158
	v_cndmask_b32_e32 v111, v173, v111, vcc
	v_cmp_lt_i32_e32 vcc, -1, v123
	v_sub_u32_e32 v117, v122, v1
	v_subrev_u32_e32 v124, 49, v123
	v_cndmask_b32_e32 v110, v173, v110, vcc
	v_cmp_lt_i32_e32 vcc, -1, v125
	v_subrev_u32_e32 v125, 48, v123
	v_add_u32_e32 v131, -16, v116
	v_cndmask_b32_e32 v113, v173, v113, vcc
	v_cmp_lt_i32_e32 vcc, -1, v126
	v_add_u32_e32 v126, -16, v117
	v_subrev_u32_e32 v132, 32, v117
	v_subrev_u32_e32 v133, 32, v116
	v_subrev_u32_e32 v135, 48, v116
	v_med3_i32 v114, v125, 0, v172
	v_med3_i32 v115, v124, 0, v172
	v_med3_i32 v122, v131, 0, v172
	v_med3_i32 v123, v126, 0, v172
	v_pk_add_f32 v[106:107], v[106:107], v[118:119]
	v_med3_i32 v118, v133, 0, v172
	v_med3_i32 v119, v132, 0, v172
	v_subrev_u32_e32 v134, 48, v117
	v_med3_i32 v116, v135, 0, v172
	v_lshl_add_u32 v114, v114, 2, v174
	v_lshl_add_u32 v115, v115, 2, v174
	v_lshl_add_u32 v122, v122, 2, v174
	v_lshl_add_u32 v123, v123, 2, v174
	v_lshl_add_u32 v118, v118, 2, v174
	v_lshl_add_u32 v119, v119, 2, v174
	v_lshl_add_u32 v136, v116, 2, v174
	v_med3_i32 v116, v134, 0, v172
	v_lshl_add_u32 v137, v116, 2, v174
	ds_read_b32 v114, v114
	ds_read_b32 v115, v115
	ds_read_b32 v116, v122
	ds_read_b32 v117, v123
	ds_read_b32 v118, v118
	ds_read_b32 v119, v119
	ds_read_b32 v122, v136
	ds_read_b32 v123, v137
	v_cndmask_b32_e32 v112, v173, v112, vcc
	s_waitcnt lgkmcnt(0)
	v_pk_add_f32 v[108:109], v[108:109], v[116:117]
	v_cmp_lt_i32_e32 vcc, -1, v126
	v_pk_add_f32 v[100:101], v[100:101], v[118:119]
	v_pk_add_f32 v[98:99], v[98:99], v[120:121]
	v_cndmask_b32_e32 v109, v173, v109, vcc
	v_cmp_lt_i32_e32 vcc, -1, v131
	v_pk_add_f32 v[104:105], v[104:105], v[122:123]
	v_pk_add_f32 v[102:103], v[102:103], v[114:115]
	v_cndmask_b32_e32 v108, v173, v108, vcc
	v_cmp_lt_i32_e32 vcc, -1, v127
	s_nop 1
	v_cndmask_b32_e32 v107, v173, v107, vcc
	v_cmp_lt_i32_e32 vcc, -1, v128
	s_nop 1
	v_cndmask_b32_e32 v106, v173, v106, vcc
	v_cmp_lt_i32_e32 vcc, -1, v132
	s_nop 1
	v_cndmask_b32_e32 v101, v173, v101, vcc
	v_cmp_lt_i32_e32 vcc, -1, v133
	s_nop 1
	v_cndmask_b32_e32 v100, v173, v100, vcc
	v_cmp_lt_i32_e32 vcc, -1, v129
	s_nop 1
	v_cndmask_b32_e32 v99, v173, v99, vcc
	v_cmp_lt_i32_e32 vcc, -1, v130
	s_nop 1
	v_cndmask_b32_e32 v98, v173, v98, vcc
	v_cmp_lt_i32_e32 vcc, -1, v134
	s_nop 1
	v_cndmask_b32_e32 v105, v173, v105, vcc
	v_cmp_lt_i32_e32 vcc, -1, v135
	s_nop 1
	v_cndmask_b32_e32 v104, v173, v104, vcc
	v_cmp_lt_i32_e32 vcc, -1, v124
	s_nop 1
	v_cndmask_b32_e32 v103, v173, v103, vcc
	v_cmp_lt_i32_e32 vcc, -1, v125
	s_nop 1
	v_cndmask_b32_e32 v102, v173, v102, vcc

; #define LAS __attribute__((address_space(3)))
; #define NEG_INF (-__builtin_inff())
; DEV void qk64(const LAS unsigned char* Kb, const AttnCtx& C, const ab8 (&qf)[2][2], f32x4 (&s)[2][4], float init0, float init1, bool a0, bool a1) {
;     ab8 k0[4], k1[4];
; #pragma unroll
;     for (int kt = 0; kt < 4; ++kt) { k0[kt] = *(const LAS ab8*)(Kb + swz(16 * kt + C.n, C.q4)); k1[kt] = *(const LAS ab8*)(Kb + swz(16 * kt + C.n, 4 + C.q4)); }
;     __builtin_amdgcn_sched_barrier(0);
; #pragma unroll
;     for (int kt = 0; kt < 4; ++kt) {
;         if (a0) { f32x4 c = {init0, init0, init0, init0}; c = __builtin_amdgcn_mfma_f32_16x16x32_bf16(k0[kt], qf[0][0], c, 0, 0, 0); s[0][kt] = __builtin_amdgcn_mfma_f32_16x16x32_bf16(k1[kt], qf[0][1], c, 0, 0, 0); }
;         if (a1) { f32x4 c = {init1, init1, init1, init1}; c = __builtin_amdgcn_mfma_f32_16x16x32_bf16(k0[kt], qf[1][0], c, 0, 0, 0); s[1][kt] = __builtin_amdgcn_mfma_f32_16x16x32_bf16(k1[kt], qf[1][1], c, 0, 0, 0); }
;     }
; }
; template <bool LUTB, bool WINLO>
; DEV void mask_bias(f32x4 (&s)[4], const AttnCtx& C, int t, int p0, int pstep, bool colok) {
; #pragma unroll
;     for (int kt = 0; kt < 4; ++kt)
; #pragma unroll
;         for (int i = 0; i < 4; ++i) { const int rel = t - (p0 + pstep * (16 * kt + 4 * C.q4 + i));
;             bool ok = colok && rel >= 0; if (WINLO) ok = ok && rel < 512;
;             float v = s[kt][i]; if (LUTB) v += C.lut[C.h * 129 + (rel < 0 ? 0 : (rel < 128 ? rel : 128))];
;             s[kt][i] = ok ? v : NEG_INF; }
; }
; DEV void attn_unit_mfma(Frame& F, int qg, int kv) {
;     ...
;         const int j = lst[1 + i]; const unsigned byte = (msk[2 * j + (w >> 2)] >> (8 * (w & 3))) & 0xffu;
;         const bool a0 = (byte & 0xfu) != 0u, a1 = (byte & 0xf0u) != 0u;
;         if (a0 || a1) {
;             const bool near = j >= cur - 2; const float bi = near ? 0.f : C.b31;
;             const bool c0 = ((byte >> (C.n >> 2)) & 1u) != 0u, c1 = ((byte >> (4 + (C.n >> 2))) & 1u) != 0u;
;     ...
;             if (a0 && a1) SEL_BODY(true, true); else if (a0) SEL_BODY(true, false); else SEL_BODY(false, true);
.LBB0_1222:
	s_cmp_ge_i32 s28, s23
	s_cbranch_scc1 .LBB0_1248
	s_waitcnt lgkmcnt(0)
	s_and_b32 s28, s100, 0xffff
	s_lshr_b32 s8, s100, 16
	s_and_b32 s9, s8, 0xff
	s_cmp_eq_u32 s9, 0
	s_cbranch_scc1 .LBB0_1248
	s_and_b32 s9, s8, 15
	s_cmp_eq_u32 s9, 0
	s_cselect_b64 s[14:15], -1, 0
	s_cmp_lg_u32 s9, 0
	s_cselect_b64 s[12:13], -1, 0
	s_and_b32 s9, s8, 0xf0
	s_cmp_lg_u32 s9, 0
	s_cselect_b64 s[16:17], -1, 0
	s_cmp_ge_i32 s28, s22
	s_cselect_b64 s[18:19], -1, 0
	s_cmp_lt_i32 s28, s22
	v_and_b32_e32 v66, s8, v206
	s_cselect_b64 vcc, -1, 0
	v_cmp_ne_u32_e64 s[10:11], 0, v66
	v_and_b32_e32 v66, s8, v207
	s_and_b64 s[16:17], s[12:13], s[16:17]
	v_cndmask_b32_e32 v216, 0, v175, vcc
	v_cmp_ne_u32_e64 s[8:9], 0, v66
	s_mov_b64 s[12:13], -1
	s_and_b64 vcc, exec, s[16:17]
	v_add3_u32 v215, s27, v199, v198
	v_add3_u32 v214, s27, v197, v198
	s_cbranch_vccnz .LBB0_1238
	ds_read_b128 v[70:73], v215 offset:32768
	ds_read_b128 v[74:77], v215 offset:34816
	ds_read_b128 v[90:93], v214 offset:32768
	ds_read_b128 v[78:81], v214 offset:34816
	ds_read_b128 v[82:85], v215 offset:36864
	ds_read_b128 v[86:89], v215 offset:38912
	ds_read_b128 v[94:97], v214 offset:36864
	ds_read_b128 v[66:69], v214 offset:38912
	s_andn2_b64 vcc, exec, s[14:15]
	s_cbranch_vccnz .LBB0_1231
	v_cmp_eq_f32_e64 s[12:13], s3, v212
	s_nop 1
	v_cndmask_b32_e64 v98, v212, 0, s[12:13]
	v_sub_f32_e32 v98, v216, v98
	v_cndmask_b32_e64 v102, v173, v98, s[8:9]
	v_mov_b32_e32 v103, v102
	v_mov_b32_e32 v104, v102
	v_mov_b32_e32 v105, v102
	s_andn2_b64 vcc, exec, s[18:19]
	s_waitcnt lgkmcnt(0)
	v_mfma_f32_16x16x32_bf16 v[98:101], v[70:73], v[10:13], v[102:105]
	v_mfma_f32_16x16x32_bf16 v[110:113], v[90:93], v[14:17], v[98:101]
	v_mfma_f32_16x16x32_bf16 v[98:101], v[74:77], v[10:13], v[102:105]
	v_mfma_f32_16x16x32_bf16 v[106:109], v[78:81], v[14:17], v[98:101]
	v_mfma_f32_16x16x32_bf16 v[98:101], v[82:85], v[10:13], v[102:105]
	v_mfma_f32_16x16x32_bf16 v[102:105], v[86:89], v[10:13], v[102:105]
	v_mfma_f32_16x16x32_bf16 v[98:101], v[94:97], v[14:17], v[98:101]
	v_mfma_f32_16x16x32_bf16 v[102:105], v[66:69], v[14:17], v[102:105]
	s_cbranch_vccnz .LBB0_1228
	s_lshl_b32 s14, s28, 6
	v_subrev_u32_e32 v122, s14, v144
	v_sub_u32_e32 v123, v122, v20
	v_add_u32_e32 v124, v122, v208
	v_add_u32_e32 v125, -3, v123
	v_add_u32_e32 v126, -2, v123
	v_subrev_u32_e32 v127, 17, v123
	v_add_u32_e32 v128, -16, v123
	v_subrev_u32_e32 v129, 33, v123
	v_subrev_u32_e32 v130, 32, v123
	v_med3_i32 v114, v123, 0, v172
	v_med3_i32 v115, v124, 0, v172
	v_med3_i32 v116, v126, 0, v172
	v_med3_i32 v117, v125, 0, v172
	v_med3_i32 v118, v128, 0, v172
	v_med3_i32 v119, v127, 0, v172
	v_med3_i32 v120, v130, 0, v172
	v_med3_i32 v121, v129, 0, v172
	v_lshl_add_u32 v114, v114, 2, v174
	v_lshl_add_u32 v115, v115, 2, v174
	v_lshl_add_u32 v116, v116, 2, v174
	v_lshl_add_u32 v117, v117, 2, v174
	v_lshl_add_u32 v118, v118, 2, v174
	v_lshl_add_u32 v119, v119, 2, v174
	v_lshl_add_u32 v120, v120, 2, v174
	v_lshl_add_u32 v121, v121, 2, v174
	ds_read_b32 v114, v114
	ds_read_b32 v115, v115
	ds_read_b32 v116, v116
	ds_read_b32 v117, v117
	ds_read_b32 v118, v118
	ds_read_b32 v119, v119
	ds_read_b32 v120, v120
	ds_read_b32 v121, v121
	s_waitcnt lgkmcnt(0)
	v_pk_add_f32 v[110:111], v[110:111], v[114:115]
	v_cmp_lt_i32_e32 vcc, -1, v124
	v_pk_add_f32 v[112:113], v[112:113], v[116:117]
	v_sub_u32_e32 v116, v122, v158
	v_cndmask_b32_e32 v111, v173, v111, vcc
	v_cmp_lt_i32_e32 vcc, -1, v123
	v_sub_u32_e32 v117, v122, v1
	v_subrev_u32_e32 v124, 49, v123
	v_cndmask_b32_e32 v110, v173, v110, vcc
	v_cmp_lt_i32_e32 vcc, -1, v125
	v_subrev_u32_e32 v125, 48, v123
	v_add_u32_e32 v131, -16, v116
	v_cndmask_b32_e32 v113, v173, v113, vcc
	v_cmp_lt_i32_e32 vcc, -1, v126
	v_add_u32_e32 v126, -16, v117
	v_subrev_u32_e32 v132, 32, v117
	v_subrev_u32_e32 v133, 32, v116
	v_subrev_u32_e32 v135, 48, v116
	v_med3_i32 v114, v125, 0, v172
	v_med3_i32 v115, v124, 0, v172
	v_med3_i32 v122, v131, 0, v172
	v_med3_i32 v123, v126, 0, v172
	v_pk_add_f32 v[106:107], v[106:107], v[118:119]
	v_med3_i32 v118, v133, 0, v172
	v_med3_i32 v119, v132, 0, v172
	v_subrev_u32_e32 v134, 48, v117
	v_med3_i32 v116, v135, 0, v172
	v_lshl_add_u32 v114, v114, 2, v174
	v_lshl_add_u32 v115, v115, 2, v174
	v_lshl_add_u32 v122, v122, 2, v174
	v_lshl_add_u32 v123, v123, 2, v174
	v_lshl_add_u32 v118, v118, 2, v174
	v_lshl_add_u32 v119, v119, 2, v174
	v_lshl_add_u32 v136, v116, 2, v174
	v_med3_i32 v116, v134, 0, v172
	v_lshl_add_u32 v137, v116, 2, v174
	ds_read_b32 v114, v114
	ds_read_b32 v115, v115
	ds_read_b32 v116, v122
	ds_read_b32 v117, v123
	ds_read_b32 v118, v118
	ds_read_b32 v119, v119
	ds_read_b32 v122, v136
	ds_read_b32 v123, v137
	v_cndmask_b32_e32 v112, v173, v112, vcc
	s_waitcnt lgkmcnt(0)
	v_pk_add_f32 v[108:109], v[108:109], v[116:117]
	v_cmp_lt_i32_e32 vcc, -1, v126
	v_pk_add_f32 v[100:101], v[100:101], v[118:119]
	v_pk_add_f32 v[98:99], v[98:99], v[120:121]
	v_cndmask_b32_e32 v109, v173, v109, vcc
	v_cmp_lt_i32_e32 vcc, -1, v131
	v_pk_add_f32 v[104:105], v[104:105], v[122:123]
	v_pk_add_f32 v[102:103], v[102:103], v[114:115]
	v_cndmask_b32_e32 v108, v173, v108, vcc
	v_cmp_lt_i32_e32 vcc, -1, v127
	s_nop 1
	v_cndmask_b32_e32 v107, v173, v107, vcc
	v_cmp_lt_i32_e32 vcc, -1, v128
	s_nop 1
	v_cndmask_b32_e32 v106, v173, v106, vcc
	v_cmp_lt_i32_e32 vcc, -1, v132
	s_nop 1
	v_cndmask_b32_e32 v101, v173, v101, vcc
	v_cmp_lt_i32_e32 vcc, -1, v133
	s_nop 1
	v_cndmask_b32_e32 v100, v173, v100, vcc
	v_cmp_lt_i32_e32 vcc, -1, v129
	s_nop 1
	v_cndmask_b32_e32 v99, v173, v99, vcc
	v_cmp_lt_i32_e32 vcc, -1, v130
	s_nop 1
	v_cndmask_b32_e32 v98, v173, v98, vcc
	v_cmp_lt_i32_e32 vcc, -1, v134
	s_nop 1
	v_cndmask_b32_e32 v105, v173, v105, vcc
	v_cmp_lt_i32_e32 vcc, -1, v135
	s_nop 1
	v_cndmask_b32_e32 v104, v173, v104, vcc
	v_cmp_lt_i32_e32 vcc, -1, v124
	s_nop 1
	v_cndmask_b32_e32 v103, v173, v103, vcc
	v_cmp_lt_i32_e32 vcc, -1, v125
	s_nop 1
	v_cndmask_b32_e32 v102, v173, v102, vcc

; template <int NB, class RowFn, class Compute>
; DEV void stream_stages_dma(Frame& F, int n, const bf16* Kg, const bf16* Vg, RowFn rowfn, Compute compute) {
;     ...
;     asm volatile("" ::: "memory"); __builtin_amdgcn_s_barrier(); asm volatile("" ::: "memory");
.LBB0_1257:
	s_setprio 0
	s_barrier

; __global__ void __launch_bounds__(512, 2) mk_fwd(Args args) {
	.amdhsa_kernel _Z6mk_fwd4Args
		.amdhsa_group_segment_fixed_size 0
		.amdhsa_private_segment_fixed_size 0
		.amdhsa_kernarg_size 512
		.amdhsa_user_sgpr_count 2
		.amdhsa_user_sgpr_dispatch_ptr 0
		.amdhsa_user_sgpr_queue_ptr 0
		.amdhsa_user_sgpr_kernarg_segment_ptr 1
		.amdhsa_user_sgpr_dispatch_id 0
		.amdhsa_user_sgpr_kernarg_preload_length 0
		.amdhsa_user_sgpr_kernarg_preload_offset 0
		.amdhsa_user_sgpr_private_segment_size 0
		.amdhsa_uses_dynamic_stack 0
		.amdhsa_enable_private_segment 0
		.amdhsa_system_sgpr_workgroup_id_x 1
		.amdhsa_system_sgpr_workgroup_id_y 0
		.amdhsa_system_sgpr_workgroup_id_z 0
		.amdhsa_system_sgpr_workgroup_info 0
		.amdhsa_system_vgpr_workitem_id 0
		.amdhsa_next_free_vgpr 256
		.amdhsa_next_free_sgpr 101
		.amdhsa_accum_offset 256
		.amdhsa_reserve_vcc 1
		.amdhsa_float_round_mode_32 0
		.amdhsa_float_round_mode_16_64 0
		.amdhsa_float_denorm_mode_32 3
		.amdhsa_float_denorm_mode_16_64 3
		.amdhsa_dx10_clamp 1
		.amdhsa_ieee_mode 1
		.amdhsa_fp16_overflow 0
		.amdhsa_tg_split 0
		.amdhsa_exception_fp_ieee_invalid_op 0
		.amdhsa_exception_fp_denorm_src 0
		.amdhsa_exception_fp_ieee_div_zero 0
		.amdhsa_exception_fp_ieee_overflow 0
		.amdhsa_exception_fp_ieee_underflow 0
		.amdhsa_exception_fp_ieee_inexact 0
		.amdhsa_exception_int_div_zero 0
	.end_amdhsa_kernel

; __global__ void __launch_bounds__(512, 2) mk_fwd(Args args) {
amdhsa.kernels:
  - .agpr_count:     0
    .args:
      - .offset:         0
        .size:           256
        .value_kind:     by_value
      - .offset:         256
        .size:           4
        .value_kind:     hidden_block_count_x
      - .offset:         260
        .size:           4
        .value_kind:     hidden_block_count_y
      - .offset:         264
        .size:           4
        .value_kind:     hidden_block_count_z
      - .offset:         268
        .size:           2
        .value_kind:     hidden_group_size_x
      - .offset:         270
        .size:           2
        .value_kind:     hidden_group_size_y
      - .offset:         272
        .size:           2
        .value_kind:     hidden_group_size_z
      - .offset:         274
        .size:           2
        .value_kind:     hidden_remainder_x
      - .offset:         276
        .size:           2
        .value_kind:     hidden_remainder_y
      - .offset:         278
        .size:           2
        .value_kind:     hidden_remainder_z
      - .offset:         296
        .size:           8
        .value_kind:     hidden_global_offset_x
      - .offset:         304
        .size:           8
        .value_kind:     hidden_global_offset_y
      - .offset:         312
        .size:           8
        .value_kind:     hidden_global_offset_z
      - .offset:         320
        .size:           2
        .value_kind:     hidden_grid_dims
      - .offset:         376
        .size:           4
        .value_kind:     hidden_dynamic_lds_size
    .group_segment_fixed_size: 0
    .kernarg_segment_align: 8
    .kernarg_segment_size: 512
    .language:       OpenCL C
    .language_version:
      - 2
      - 0
    .max_flat_workgroup_size: 512
    .name:           _Z6mk_fwd4Args
    .private_segment_fixed_size: 0
    .sgpr_count:     107
    .sgpr_spill_count: 160
    .symbol:         _Z6mk_fwd4Args.kd
    .uniform_work_group_size: 1
    .uses_dynamic_stack: false
    .vgpr_count:     256
    .vgpr_spill_count: 0
    .wavefront_size: 64
